# v035 + P row sums in the diff tile loops by v_dot2c_f32_bf16 partial sums instead of the P x ones MFMA (4 of 28 MFMAs per tile removed)
# baseline (speedup 1.0000x reference)
; #define LAS __attribute__((address_space(3)))
; __device__ __forceinline__ float ex2(float v) { return __builtin_amdgcn_exp2f(v); }
; #define MFMA32(a, b, c) __builtin_amdgcn_mfma_f32_32x32x16_bf16((a), (b), (c), 0, 0, 0)
; #define SCHEDB() __builtin_amdgcn_sched_barrier(0)
; __device__ __forceinline__ void diff_unit(const Params& p, LAS unsigned char* lds, int b, int h, int qb, float lam) {
;     ...
;         const bf16_t* Kg0 = (const bf16_t*)(p.ws + WS_KD) + ((size_t)(2 * h + mp) * MT + rowbase) * 64;
;         tile_dma<64>(Kg0, Vg0, lds + A_KOFF, lds + A_VOFF, wid, lane);
;         const bf16_t* qp = QK + (rowbase + q0 + c) * 4096 + h * 128 + 64 * mp + hh * 8;
;         bf16x8 qf[4];
; #pragma unroll
;         for (int ks = 0; ks < 4; ++ks) qf[ks] = *(const bf16x8*)(qp + 16 * ks);
; #pragma unroll
;         for (int db = 0; db < 4; ++db) O[db] = (f32x16){};
;         f32x16 L = (f32x16){};
;         f32x16 negm = (f32x16){};
;         float m = 0.f;
;         asm volatile("s_waitcnt vmcnt(0)" ::: "memory");
;         __syncthreads();
;     ...
; #pragma unroll
;                 for (int r = 0; r < 16; ++r) s0[r] = ex2(s0[r]);
; #pragma unroll
;                 for (int g = 0; g < 4; ++g) {
;                     const int co = ((4 * (g >> 1) + (g & 1)) ^ xv) << 4;
;                     bf16x8 vf[4];
; #pragma unroll
;                     for (int db = 0; db < 4; ++db) vf[db] = *(const LAS bf16x8*)(vb + db * 4096 + co);
;                     const bf16x8 pf = pack8((g >> 1) ? s1 : s0, 8 * (g & 1));
; #pragma unroll
;                     for (int db = 0; db < 4; ++db) O[db] = MFMA32(pf, vf[db], O[db]);
;                     L = MFMA32(pf, ones, L);
;                     if (g < 2) {
; #pragma unroll
;                         for (int r = 0; r < 8; ++r) s1[8 * g + r] = ex2(s1[8 * g + r]);
;                     }
;                     SCHEDB();
;                 }
.LBB0_282:
	s_lshl_b32 s75, s0, 7
	s_lshl_b32 s0, s72, 21
	v_sub_u32_e32 v2, v196, v112
	s_and_b32 s9, s0, 0x3800000
	s_lshl_b32 s0, s72, 15
	v_subrev_u32_e32 v208, 64, v2
	v_add_u32_e32 v2, s23, v117
	s_and_b32 s6, s0, 0x700000
	v_ashrrev_i32_e32 v3, 31, v2
	s_or_b32 s6, s9, s6
	v_lshlrev_b64 v[4:5], 7, v[2:3]
	v_lshl_add_u64 v[4:5], s[6:7], 0, v[4:5]
	v_and_b32_e32 v3, 7, v118
	v_add_u32_e32 v2, 8, v2
	v_lshl_or_b32 v4, v3, 4, v4
	v_ashrrev_i32_e32 v3, 31, v2
	v_lshlrev_b64 v[2:3], 7, v[2:3]
	v_lshl_add_u64 v[166:167], s[20:21], 0, v[4:5]
	v_lshl_add_u64 v[2:3], s[6:7], 0, v[2:3]
	v_and_b32_e32 v4, 7, v119
	s_add_i32 s3, s22, s3
	s_lshl_b32 s0, s72, 14
	v_lshl_or_b32 v2, v4, 4, v2
	s_add_i32 s3, s3, s1
	s_and_b32 s10, s0, 0x380000
	v_lshl_add_u64 v[168:169], s[20:21], 0, v[2:3]
	v_add_u32_e32 v2, s3, v114
	s_or_b32 s6, s9, s10
	v_add_lshl_u32 v2, v2, v115, 7
	v_mov_b32_e32 v3, v1
	s_waitcnt vmcnt(0)
	s_mov_b32 s67, s7
	v_lshl_add_u64 v[180:181], s[6:7], 0, v[2:3]
	v_and_b32_e32 v2, 7, v116
	s_lshl_b64 s[4:5], s[66:67], 16
	v_lshl_or_b32 v180, v2, 4, v180
	v_lshlrev_b32_e32 v0, 6, v120
	s_lshl_b32 s80, s88, 11
	s_or_b32 s0, s4, 0x8000
	v_lshl_add_u64 v[2:3], s[38:39], 0, v[180:181]
	s_mov_b32 s1, 1
	s_mov_b64 s[4:5], 0
	s_mov_b32 s3, s77
	s_waitcnt vmcnt(0) lgkmcnt(0)
	s_barrier
	v_mov_b32_e32 v192, 0
	v_mov_b32_e32 v193, 0
	s_branch .LBB0_285
.LBB0_283:
	v_add_u32_e32 v244, v4, v198
	ds_read_b128 v[240:243], v244 offset:32768
	ds_read_b128 v[236:239], v244 offset:36864
	ds_read_b128 v[232:235], v244 offset:40960
	ds_read_b128 v[228:231], v244 offset:45056
	v_add_u32_e32 v244, v4, v199
	ds_read_b128 v[216:219], v244 offset:32768
	v_exp_f32_e32 v5, v128
	v_exp_f32_e32 v14, v129
	v_exp_f32_e32 v15, v130
	v_exp_f32_e32 v183, v131
	v_exp_f32_e32 v184, v132
	v_exp_f32_e32 v185, v133
	v_exp_f32_e32 v186, v134
	v_exp_f32_e32 v187, v135
	v_exp_f32_e32 v188, v136
	v_exp_f32_e32 v189, v137
	v_exp_f32_e32 v209, v138
	v_exp_f32_e32 v210, v139
	v_cvt_pk_bf16_f32 v136, v5, v14
	v_cvt_pk_bf16_f32 v137, v15, v183
	v_cvt_pk_bf16_f32 v138, v184, v185
	v_cvt_pk_bf16_f32 v139, v186, v187
	s_mov_b32 s9, s8
	s_waitcnt lgkmcnt(4)
	v_mfma_f32_32x32x16_bf16 v[16:31], v[136:139], v[240:243], v[16:31]
	ds_read_b128 v[240:243], v244 offset:36864
	s_mov_b32 s10, s8
	s_mov_b32 s11, s8
	v_mov_b64_e32 v[6:7], s[8:9]
	v_mov_b64_e32 v[8:9], s[10:11]
	v_exp_f32_e32 v140, v140
	v_exp_f32_e32 v141, v141
	v_exp_f32_e32 v142, v142
	s_waitcnt lgkmcnt(4)
	v_mfma_f32_32x32x16_bf16 v[32:47], v[136:139], v[236:239], v[32:47]
	ds_read_b128 v[236:239], v244 offset:40960
	v_exp_f32_e32 v143, v143
	v_exp_f32_e32 v5, v112
	v_exp_f32_e32 v14, v113
	v_exp_f32_e32 v15, v114
	v_exp_f32_e32 v116, v116
	v_exp_f32_e32 v117, v117
	v_exp_f32_e32 v118, v118
	s_waitcnt lgkmcnt(4)
	v_mfma_f32_32x32x16_bf16 v[48:63], v[136:139], v[232:235], v[48:63]
	ds_read_b128 v[232:235], v244 offset:45056
	v_exp_f32_e32 v128, v115
	v_exp_f32_e32 v119, v119
	s_waitcnt lgkmcnt(4)
	v_mfma_f32_32x32x16_bf16 v[64:79], v[136:139], v[228:231], v[64:79]
	v_add_u32_e32 v244, v4, v200
	ds_read_b128 v[228:231], v244 offset:32768
	v_dot2c_f32_bf16 v192, s8, v136
	v_dot2c_f32_bf16 v193, s8, v137
	v_dot2c_f32_bf16 v192, s8, v138
	v_dot2c_f32_bf16 v193, s8, v139
	v_cvt_pk_bf16_f32 v10, v188, v189
	v_cvt_pk_bf16_f32 v11, v209, v210
	v_cvt_pk_bf16_f32 v12, v140, v141
	v_cvt_pk_bf16_f32 v13, v142, v143
	v_exp_f32_e32 v120, v120
	s_waitcnt lgkmcnt(4)
	v_mfma_f32_32x32x16_bf16 v[16:31], v[10:13], v[216:219], v[16:31]
	ds_read_b128 v[216:219], v244 offset:36864
	v_exp_f32_e32 v121, v121
	v_exp_f32_e32 v122, v122
	v_exp_f32_e32 v123, v123
	v_exp_f32_e32 v124, v124
	v_exp_f32_e32 v125, v125
	v_exp_f32_e32 v126, v126
	s_waitcnt lgkmcnt(4)
	v_mfma_f32_32x32x16_bf16 v[32:47], v[10:13], v[240:243], v[32:47]
	ds_read_b128 v[240:243], v244 offset:40960
	v_exp_f32_e32 v127, v127
	s_waitcnt lgkmcnt(4)
	v_mfma_f32_32x32x16_bf16 v[48:63], v[10:13], v[236:239], v[48:63]
	ds_read_b128 v[236:239], v244 offset:45056
	s_waitcnt lgkmcnt(4)
	v_mfma_f32_32x32x16_bf16 v[64:79], v[10:13], v[232:235], v[64:79]
	v_add_u32_e32 v244, v4, v201
	ds_read_b128 v[232:235], v244 offset:32768
	v_dot2c_f32_bf16 v192, s8, v10
	v_dot2c_f32_bf16 v193, s8, v11
	v_dot2c_f32_bf16 v192, s8, v12
	v_dot2c_f32_bf16 v193, s8, v13
	v_cvt_pk_bf16_f32 v10, v5, v14
	v_cvt_pk_bf16_f32 v11, v15, v128
	v_cvt_pk_bf16_f32 v12, v116, v117
	v_cvt_pk_bf16_f32 v13, v118, v119
	s_waitcnt lgkmcnt(4)
	s_nop 0
	v_mfma_f32_32x32x16_bf16 v[16:31], v[10:13], v[228:231], v[16:31]
	ds_read_b128 v[228:231], v244 offset:36864
	s_waitcnt lgkmcnt(4)
	v_mfma_f32_32x32x16_bf16 v[32:47], v[10:13], v[216:219], v[32:47]
	ds_read_b128 v[216:219], v244 offset:40960
	s_waitcnt lgkmcnt(4)
	v_mfma_f32_32x32x16_bf16 v[48:63], v[10:13], v[240:243], v[48:63]
	ds_read_b128 v[240:243], v244 offset:45056
	s_waitcnt lgkmcnt(4)
	v_mfma_f32_32x32x16_bf16 v[64:79], v[10:13], v[236:239], v[64:79]
	v_dot2c_f32_bf16 v192, s8, v10
	v_dot2c_f32_bf16 v193, s8, v11
	v_dot2c_f32_bf16 v192, s8, v12
	v_dot2c_f32_bf16 v193, s8, v13
	v_add_u32_e32 v4, v4, v201
	v_cvt_pk_bf16_f32 v10, v120, v121
	v_cvt_pk_bf16_f32 v11, v122, v123
	v_cvt_pk_bf16_f32 v12, v124, v125
	v_cvt_pk_bf16_f32 v13, v126, v127
	s_waitcnt lgkmcnt(3)
	s_nop 0
	v_mfma_f32_32x32x16_bf16 v[16:31], v[10:13], v[232:235], v[16:31]
	s_waitcnt lgkmcnt(2)
	v_mfma_f32_32x32x16_bf16 v[32:47], v[10:13], v[228:231], v[32:47]
	s_waitcnt lgkmcnt(1)
	v_mfma_f32_32x32x16_bf16 v[48:63], v[10:13], v[216:219], v[48:63]
	s_waitcnt lgkmcnt(0)
	v_mfma_f32_32x32x16_bf16 v[64:79], v[10:13], v[240:243], v[64:79]
	v_dot2c_f32_bf16 v192, s8, v10
	v_dot2c_f32_bf16 v193, s8, v11
	v_dot2c_f32_bf16 v192, s8, v12
	v_dot2c_f32_bf16 v193, s8, v13

; __device__ __forceinline__ float ex2(float v) { return __builtin_amdgcn_exp2f(v); }
; __device__ __forceinline__ int crow(int r, int h) { return (r & 3) + 8 * (r >> 2) + 4 * h; }
; #define MX3(a, b, c) __builtin_fmaxf(__builtin_fmaxf((a), (b)), (c))
; __device__ __forceinline__ void diff_unit(const Params& p, LAS unsigned char* lds, int b, int h, int qb, float lam) {
;     ...
;                 float mx;
;                 { float a0 = MX3(s0[0], s0[1], s1[0]), a1 = MX3(s0[2], s0[3], s1[1]); a0 = MX3(a0, s1[2], s1[3]);
; #pragma unroll
;                   for (int r = 4; r < 16; r += 4) { a0 = MX3(a0, s0[r], s0[r + 1]); a1 = MX3(a1, s0[r + 2], s0[r + 3]); a0 = MX3(a0, s1[r], s1[r + 1]); a1 = MX3(a1, s1[r + 2], s1[r + 3]); }
;                   mx = fmaxf(a0, a1); }
;                 { auto rr = __builtin_amdgcn_permlane32_swap(__float_as_uint(mx), __float_as_uint(mx), false, false); mx = fmaxf(__uint_as_float(rr[0]), __uint_as_float(rr[1])); }
;                 const bool first = (jt == 0);
;                 if (first || __any(mx > 8.0f)) {
;                     const float dl = first ? mx : fmaxf(mx, 0.f);
;                     m += dl;
; #pragma unroll
;                     for (int r = 0; r < 16; ++r) { s0[r] -= dl; s1[r] -= dl; }
; #pragma unroll
;                     for (int r = 0; r < 16; ++r) negm[r] = -m;
;                     if (!first) {
;                         const float alpha = ex2(-dl);
;                         int hl = hh; asm volatile("" : "+v"(hl));
; #pragma unroll
;                         for (int r = 0; r < 16; ++r) { const float a = __shfl(alpha, crow(r, hl)); L[r] *= a;
; #pragma unroll
;                             for (int db = 0; db < 4; ++db) O[db][r] *= a; }
;                     }
;                 }
.LBB0_288:
	s_nop 7
	v_max_f32_e32 v5, v129, v129
	v_max_f32_e32 v6, v128, v128
	v_max_f32_e32 v5, v6, v5
	v_max3_f32 v6, v130, v131, v113
	v_max3_f32 v5, v5, v112, v114
	v_max3_f32 v5, v5, v115, v132
	v_max3_f32 v6, v6, v134, v135
	v_max3_f32 v5, v5, v133, v116
	v_max3_f32 v6, v6, v118, v119
	v_max3_f32 v5, v5, v117, v136
	v_max3_f32 v6, v6, v138, v139
	v_max3_f32 v5, v5, v137, v120
	v_max3_f32 v6, v6, v122, v123
	v_max3_f32 v5, v5, v121, v140
	v_max3_f32 v6, v6, v142, v143
	v_max3_f32 v5, v5, v141, v124
	v_max3_f32 v6, v6, v126, v127
	v_max3_f32 v5, v5, v125, v6
	v_mov_b32_e32 v6, v5
	s_nop 1
	v_permlane32_swap_b32_e32 v5, v6
	v_max_f32_e32 v6, v6, v6
	v_max_f32_e32 v5, v5, v5
	v_max_f32_e32 v5, v5, v6
	v_cmp_lt_f32_e32 vcc, s70, v5
	s_cbranch_vccz .LBB0_283
	v_max_f32_e32 v5, v5, v5
	v_max_f32_e32 v6, 0, v5
	v_pk_add_f32 v[112:113], v[112:113], v[6:7] op_sel_hi:[1,0] neg_lo:[0,1] neg_hi:[0,1]
	v_pk_add_f32 v[114:115], v[114:115], v[6:7] op_sel_hi:[1,0] neg_lo:[0,1] neg_hi:[0,1]
	v_pk_add_f32 v[116:117], v[116:117], v[6:7] op_sel_hi:[1,0] neg_lo:[0,1] neg_hi:[0,1]
	v_pk_add_f32 v[118:119], v[118:119], v[6:7] op_sel_hi:[1,0] neg_lo:[0,1] neg_hi:[0,1]
	v_pk_add_f32 v[120:121], v[120:121], v[6:7] op_sel_hi:[1,0] neg_lo:[0,1] neg_hi:[0,1]
	v_pk_add_f32 v[122:123], v[122:123], v[6:7] op_sel_hi:[1,0] neg_lo:[0,1] neg_hi:[0,1]
	v_pk_add_f32 v[124:125], v[124:125], v[6:7] op_sel_hi:[1,0] neg_lo:[0,1] neg_hi:[0,1]
	v_pk_add_f32 v[126:127], v[126:127], v[6:7] op_sel_hi:[1,0] neg_lo:[0,1] neg_hi:[0,1]
	v_pk_add_f32 v[128:129], v[128:129], v[6:7] op_sel_hi:[1,0] neg_lo:[0,1] neg_hi:[0,1]
	v_pk_add_f32 v[130:131], v[130:131], v[6:7] op_sel_hi:[1,0] neg_lo:[0,1] neg_hi:[0,1]
	v_pk_add_f32 v[132:133], v[132:133], v[6:7] op_sel_hi:[1,0] neg_lo:[0,1] neg_hi:[0,1]
	v_pk_add_f32 v[134:135], v[134:135], v[6:7] op_sel_hi:[1,0] neg_lo:[0,1] neg_hi:[0,1]
	v_pk_add_f32 v[136:137], v[136:137], v[6:7] op_sel_hi:[1,0] neg_lo:[0,1] neg_hi:[0,1]
	v_pk_add_f32 v[138:139], v[138:139], v[6:7] op_sel_hi:[1,0] neg_lo:[0,1] neg_hi:[0,1]
	v_pk_add_f32 v[140:141], v[140:141], v[6:7] op_sel_hi:[1,0] neg_lo:[0,1] neg_hi:[0,1]
	v_pk_add_f32 v[142:143], v[142:143], v[6:7] op_sel_hi:[1,0] neg_lo:[0,1] neg_hi:[0,1]
	v_add_f32_e32 v165, v165, v6
	v_exp_f32_e64 v5, -v6
	v_mov_b32_e32 v6, v195
	v_xor_b32_e32 v96, 0x80000000, v165
	v_lshlrev_b32_e32 v13, 2, v6
	v_mul_f32_e32 v192, v192, v5
	v_mul_f32_e32 v193, v193, v5
	v_add_u32_e32 v14, 11, v13
	v_and_or_b32 v14, v14, 63, v194
	v_and_or_b32 v6, v13, 60, v194
	v_add_u32_e32 v10, 8, v13
	v_add_u32_e32 v11, 9, v13
	v_add_u32_e32 v12, 10, v13
	v_lshlrev_b32_e32 v183, 2, v14
	v_add_u32_e32 v14, 16, v13
	v_add_u32_e32 v15, 17, v13
	v_add_u32_e32 v184, 18, v13
	v_add_u32_e32 v185, 19, v13
	v_add_u32_e32 v186, 24, v13
	v_add_u32_e32 v187, 25, v13
	v_add_u32_e32 v188, 26, v13
	v_add_u32_e32 v13, 27, v13
	v_and_or_b32 v10, v10, 60, v194
	v_and_or_b32 v11, v11, 61, v194
	v_and_or_b32 v12, v12, 62, v194
	v_and_or_b32 v14, v14, 60, v194
	v_and_or_b32 v15, v15, 61, v194
	v_and_or_b32 v184, v184, 62, v194
	v_and_or_b32 v185, v185, 63, v194
	v_and_or_b32 v186, v186, 60, v194
	v_and_or_b32 v187, v187, 61, v194
	v_and_or_b32 v188, v188, 62, v194
	v_and_or_b32 v13, v13, 63, v194
	v_lshlrev_b32_e32 v9, 2, v6
	v_lshlrev_b32_e32 v10, 2, v10
	v_lshlrev_b32_e32 v11, 2, v11
	v_lshlrev_b32_e32 v12, 2, v12
	v_lshlrev_b32_e32 v14, 2, v14
	v_lshlrev_b32_e32 v15, 2, v15
	v_lshlrev_b32_e32 v184, 2, v184
	v_lshlrev_b32_e32 v185, 2, v185
	v_lshlrev_b32_e32 v186, 2, v186
	v_lshlrev_b32_e32 v187, 2, v187
	v_lshlrev_b32_e32 v188, 2, v188
	v_lshlrev_b32_e32 v13, 2, v13
	ds_bpermute_b32 v6, v9, v5
	ds_bpermute_b32 v7, v9, v5 offset:4
	ds_bpermute_b32 v8, v9, v5 offset:8
	ds_bpermute_b32 v9, v9, v5 offset:12
	ds_bpermute_b32 v10, v10, v5
	ds_bpermute_b32 v11, v11, v5
	ds_bpermute_b32 v12, v12, v5
	ds_bpermute_b32 v14, v14, v5
	ds_bpermute_b32 v184, v184, v5
	ds_bpermute_b32 v186, v186, v5
	ds_bpermute_b32 v188, v188, v5
	ds_bpermute_b32 v189, v13, v5
	ds_bpermute_b32 v187, v187, v5
	ds_bpermute_b32 v185, v185, v5
	ds_bpermute_b32 v15, v15, v5
	ds_bpermute_b32 v13, v183, v5
	v_mov_b32_e32 v97, v96
	v_mov_b32_e32 v98, v96
	v_mov_b32_e32 v99, v96
	v_mov_b32_e32 v100, v96
	v_mov_b32_e32 v101, v96
	v_mov_b32_e32 v102, v96
	v_mov_b32_e32 v103, v96
	v_mov_b32_e32 v104, v96
	v_mov_b32_e32 v105, v96
	v_mov_b32_e32 v106, v96
	v_mov_b32_e32 v107, v96
	v_mov_b32_e32 v108, v96
	v_mov_b32_e32 v109, v96
	v_mov_b32_e32 v110, v96
	v_mov_b32_e32 v111, v96
	s_waitcnt lgkmcnt(0)
	v_pk_mul_f32 v[30:31], v[30:31], v[188:189]
	v_pk_mul_f32 v[28:29], v[28:29], v[186:187]
	v_pk_mul_f32 v[26:27], v[26:27], v[184:185]
	v_pk_mul_f32 v[24:25], v[24:25], v[14:15]
	v_pk_mul_f32 v[22:23], v[22:23], v[12:13]
	v_pk_mul_f32 v[20:21], v[20:21], v[10:11]
	v_pk_mul_f32 v[18:19], v[18:19], v[8:9]
	v_pk_mul_f32 v[16:17], v[16:17], v[6:7]
	v_pk_mul_f32 v[46:47], v[46:47], v[188:189]
	v_pk_mul_f32 v[44:45], v[44:45], v[186:187]
	v_pk_mul_f32 v[42:43], v[42:43], v[184:185]
	v_pk_mul_f32 v[40:41], v[40:41], v[14:15]
	v_pk_mul_f32 v[38:39], v[38:39], v[12:13]
	v_pk_mul_f32 v[36:37], v[36:37], v[10:11]
	v_pk_mul_f32 v[34:35], v[34:35], v[8:9]
	v_pk_mul_f32 v[32:33], v[32:33], v[6:7]
	v_pk_mul_f32 v[62:63], v[62:63], v[188:189]
	v_pk_mul_f32 v[60:61], v[60:61], v[186:187]
	v_pk_mul_f32 v[58:59], v[58:59], v[184:185]
	v_pk_mul_f32 v[56:57], v[56:57], v[14:15]
	v_pk_mul_f32 v[54:55], v[54:55], v[12:13]
	v_pk_mul_f32 v[52:53], v[52:53], v[10:11]
	v_pk_mul_f32 v[50:51], v[50:51], v[8:9]
	v_pk_mul_f32 v[48:49], v[48:49], v[6:7]
	v_pk_mul_f32 v[78:79], v[78:79], v[188:189]
	v_pk_mul_f32 v[76:77], v[76:77], v[186:187]
	v_pk_mul_f32 v[74:75], v[74:75], v[184:185]
	v_pk_mul_f32 v[72:73], v[72:73], v[14:15]
	v_pk_mul_f32 v[70:71], v[70:71], v[12:13]
	v_pk_mul_f32 v[68:69], v[68:69], v[10:11]
	v_pk_mul_f32 v[66:67], v[66:67], v[8:9]
	v_pk_mul_f32 v[64:65], v[64:65], v[6:7]
	v_pk_mul_f32 v[94:95], v[94:95], v[188:189]
	v_pk_mul_f32 v[92:93], v[92:93], v[186:187]
	v_pk_mul_f32 v[90:91], v[90:91], v[184:185]
	v_pk_mul_f32 v[88:89], v[88:89], v[14:15]
	v_pk_mul_f32 v[86:87], v[86:87], v[12:13]
	v_pk_mul_f32 v[84:85], v[84:85], v[10:11]
	v_pk_mul_f32 v[82:83], v[82:83], v[8:9]
	v_pk_mul_f32 v[80:81], v[80:81], v[6:7]
	s_branch .LBB0_283
; #define MFMA32(a, b, c) __builtin_amdgcn_mfma_f32_32x32x16_bf16((a), (b), (c), 0, 0, 0)
; __device__ __forceinline__ void diff_unit(const Params& p, LAS unsigned char* lds, int b, int h, int qb, float lam) {
;     ...
;                     L = MFMA32(pf, ones, L);
;     ...
; #pragma unroll
;         for (int r = 0; r < 16; ++r) { const float a = (mp == 0 ? 1.0f : lam) / L[r];
.Llsum_fold0:
	v_add_f32_e32 v192, v192, v193
	v_xor_b32_e32 v5, 32, v163
	v_lshlrev_b32_e32 v5, 2, v5
	ds_bpermute_b32 v6, v5, v192
	v_lshlrev_b32_e32 v7, 4, v195
	s_waitcnt lgkmcnt(0)
	v_add_f32_e32 v192, v192, v6
	ds_bpermute_b32 v8, v7, v192
	ds_bpermute_b32 v9, v7, v192 offset:4
	ds_bpermute_b32 v10, v7, v192 offset:8
	ds_bpermute_b32 v11, v7, v192 offset:12
	ds_bpermute_b32 v12, v7, v192 offset:32
	ds_bpermute_b32 v13, v7, v192 offset:36
	ds_bpermute_b32 v14, v7, v192 offset:40
	ds_bpermute_b32 v15, v7, v192 offset:44
	ds_bpermute_b32 v228, v7, v192 offset:64
	ds_bpermute_b32 v229, v7, v192 offset:68
	ds_bpermute_b32 v230, v7, v192 offset:72
	ds_bpermute_b32 v231, v7, v192 offset:76
	ds_bpermute_b32 v232, v7, v192 offset:96
	ds_bpermute_b32 v233, v7, v192 offset:100
	ds_bpermute_b32 v234, v7, v192 offset:104
	ds_bpermute_b32 v235, v7, v192 offset:108
	s_waitcnt lgkmcnt(0)
	v_add_f32_e32 v80, v80, v8
	v_add_f32_e32 v81, v81, v9
	v_add_f32_e32 v82, v82, v10
	v_add_f32_e32 v83, v83, v11
	v_add_f32_e32 v84, v84, v12
	v_add_f32_e32 v85, v85, v13
	v_add_f32_e32 v86, v86, v14
	v_add_f32_e32 v87, v87, v15
	v_add_f32_e32 v88, v88, v228
	v_add_f32_e32 v89, v89, v229
	v_add_f32_e32 v90, v90, v230
	v_add_f32_e32 v91, v91, v231
	v_add_f32_e32 v92, v92, v232
	v_add_f32_e32 v93, v93, v233
	v_add_f32_e32 v94, v94, v234
	v_add_f32_e32 v95, v95, v235
	s_branch .LBB0_290

; #define LAS __attribute__((address_space(3)))
; __device__ __forceinline__ float ex2(float v) { return __builtin_amdgcn_exp2f(v); }
; #define MFMA32(a, b, c) __builtin_amdgcn_mfma_f32_32x32x16_bf16((a), (b), (c), 0, 0, 0)
; #define SCHEDB() __builtin_amdgcn_sched_barrier(0)
; __device__ __forceinline__ void diff_unit(const Params& p, LAS unsigned char* lds, int b, int h, int qb, float lam) {
;     ...
;         const bf16_t* Kg0 = (const bf16_t*)(p.ws + WS_KD) + ((size_t)(2 * h + mp) * MT + rowbase) * 64;
;         tile_dma<64>(Kg0, Vg0, lds + A_KOFF, lds + A_VOFF, wid, lane);
;         const bf16_t* qp = QK + (rowbase + q0 + c) * 4096 + h * 128 + 64 * mp + hh * 8;
;         bf16x8 qf[4];
; #pragma unroll
;         for (int ks = 0; ks < 4; ++ks) qf[ks] = *(const bf16x8*)(qp + 16 * ks);
; #pragma unroll
;         for (int db = 0; db < 4; ++db) O[db] = (f32x16){};
;         f32x16 L = (f32x16){};
;         f32x16 negm = (f32x16){};
;         float m = 0.f;
;         asm volatile("s_waitcnt vmcnt(0)" ::: "memory");
;         __syncthreads();
;     ...
; #pragma unroll
;                 for (int r = 0; r < 16; ++r) s0[r] = ex2(s0[r]);
; #pragma unroll
;                 for (int g = 0; g < 4; ++g) {
;                     const int co = ((4 * (g >> 1) + (g & 1)) ^ xv) << 4;
;                     bf16x8 vf[4];
; #pragma unroll
;                     for (int db = 0; db < 4; ++db) vf[db] = *(const LAS bf16x8*)(vb + db * 4096 + co);
;                     const bf16x8 pf = pack8((g >> 1) ? s1 : s0, 8 * (g & 1));
; #pragma unroll
;                     for (int db = 0; db < 4; ++db) O[db] = MFMA32(pf, vf[db], O[db]);
;                     L = MFMA32(pf, ones, L);
;                     if (g < 2) {
; #pragma unroll
;                         for (int r = 0; r < 8; ++r) s1[8 * g + r] = ex2(s1[8 * g + r]);
;                     }
;                     SCHEDB();
;                 }
.LBB0_302:
	s_mov_b64 s[0:1], 0x1000
	v_lshl_add_u64 v[186:187], v[164:165], 0, s[0:1]
	s_mov_b64 s[0:1], 0x1100
	v_lshl_add_u64 v[4:5], v[164:165], 0, s[0:1]
	s_mov_b64 s[0:1], 0x1200
	v_lshl_add_u64 v[6:7], v[164:165], 0, s[0:1]
	s_mov_b64 s[0:1], 0x1300
	v_lshl_add_u64 v[176:177], v[164:165], 0, s[0:1]
	s_mov_b64 s[0:1], 0x1400
	v_lshl_add_u64 v[178:179], v[164:165], 0, s[0:1]
	s_mov_b64 s[0:1], 0x1500
	v_lshl_add_u64 v[182:183], v[164:165], 0, s[0:1]
	s_mov_b64 s[0:1], 0x1600
	v_lshl_add_u64 v[184:185], v[164:165], 0, s[0:1]
	s_mov_b64 s[0:1], 0x1700
	v_lshl_add_u64 v[8:9], v[164:165], 0, s[0:1]
	s_mov_b64 s[0:1], 0x1800
	s_waitcnt vmcnt(0)
	v_lshl_add_u64 v[188:189], v[164:165], 0, s[0:1]
	s_mov_b64 s[0:1], 0x1900
	v_lshl_add_u64 v[10:11], v[164:165], 0, s[0:1]
	v_lshl_add_u64 v[12:13], v[164:165], 0, s[46:47]
	v_lshl_add_u64 v[14:15], v[164:165], 0, s[48:49]
	v_lshl_add_u64 v[170:171], v[164:165], 0, s[50:51]
	v_lshl_add_u64 v[172:173], v[164:165], 0, s[52:53]
	v_lshl_add_u64 v[174:175], v[164:165], 0, s[58:59]
	v_lshl_add_u64 v[2:3], v[164:165], 0, s[62:63]
	v_lshl_add_u64 v[180:181], s[40:41], 0, v[180:181]
	s_mov_b32 s0, 1
	s_mov_b64 s[64:65], 0
	s_waitcnt vmcnt(0) lgkmcnt(0)
	s_barrier
	v_mov_b32_e32 v192, 0
	v_mov_b32_e32 v193, 0
	s_branch .LBB0_305
.LBB0_303:
	v_add_u32_e32 v244, v0, v198
	ds_read_b128 v[240:243], v244 offset:32768
	ds_read_b128 v[236:239], v244 offset:36864
	ds_read_b128 v[232:235], v244 offset:40960
	ds_read_b128 v[228:231], v244 offset:45056
	v_add_u32_e32 v244, v0, v199
	ds_read_b128 v[184:187], v244 offset:32768
	ds_read_b128 v[176:179], v244 offset:36864
	v_exp_f32_e32 v128, v128
	v_exp_f32_e32 v129, v129
	v_exp_f32_e32 v130, v130
	v_exp_f32_e32 v131, v131
	v_exp_f32_e32 v132, v132
	v_exp_f32_e32 v133, v133
	v_exp_f32_e32 v134, v134
	v_exp_f32_e32 v135, v135
	v_cvt_pk_bf16_f32 v128, v128, v129
	v_cvt_pk_bf16_f32 v129, v130, v131
	v_cvt_pk_bf16_f32 v130, v132, v133
	v_cvt_pk_bf16_f32 v131, v134, v135
	s_waitcnt lgkmcnt(5)
	s_nop 0
	v_mfma_f32_32x32x16_bf16 v[16:31], v[128:131], v[240:243], v[16:31]
	ds_read_b128 v[240:243], v244 offset:40960
	s_mov_b32 s10, s8
	s_mov_b32 s11, s8
	s_mov_b32 s9, s8
	v_exp_f32_e32 v136, v136
	v_exp_f32_e32 v137, v137
	v_exp_f32_e32 v138, v138
	s_waitcnt lgkmcnt(5)
	v_mfma_f32_32x32x16_bf16 v[32:47], v[128:131], v[236:239], v[32:47]
	ds_read_b128 v[236:239], v244 offset:45056
	v_exp_f32_e32 v139, v139
	v_exp_f32_e32 v140, v140
	v_exp_f32_e32 v141, v141
	v_exp_f32_e32 v142, v142
	v_exp_f32_e32 v143, v143
	v_exp_f32_e32 v213, v112
	s_waitcnt lgkmcnt(5)
	v_mfma_f32_32x32x16_bf16 v[48:63], v[128:131], v[232:235], v[48:63]
	v_add_u32_e32 v244, v0, v200
	ds_read_b128 v[232:235], v244 offset:32768
	v_mov_b64_e32 v[134:135], s[10:11]
	v_mov_b64_e32 v[132:133], s[8:9]
	v_exp_f32_e32 v218, v117
	v_exp_f32_e32 v219, v118
	v_exp_f32_e32 v220, v119
	s_waitcnt lgkmcnt(5)
	v_mfma_f32_32x32x16_bf16 v[64:79], v[128:131], v[228:231], v[64:79]
	ds_read_b128 v[228:231], v244 offset:36864
	v_exp_f32_e32 v214, v113
	v_exp_f32_e32 v215, v114
	v_exp_f32_e32 v216, v115
	v_exp_f32_e32 v217, v116
	v_dot2c_f32_bf16 v192, s8, v128
	v_dot2c_f32_bf16 v193, s8, v129
	v_dot2c_f32_bf16 v192, s8, v130
	v_dot2c_f32_bf16 v193, s8, v131
	v_cvt_pk_bf16_f32 v112, v136, v137
	v_cvt_pk_bf16_f32 v113, v138, v139
	v_cvt_pk_bf16_f32 v114, v140, v141
	v_cvt_pk_bf16_f32 v115, v142, v143
	s_waitcnt lgkmcnt(5)
	s_nop 0
	v_mfma_f32_32x32x16_bf16 v[16:31], v[112:115], v[184:187], v[16:31]
	ds_read_b128 v[184:187], v244 offset:40960
	v_exp_f32_e32 v124, v124
	v_exp_f32_e32 v125, v125
	v_exp_f32_e32 v126, v126
	v_exp_f32_e32 v127, v127
	s_waitcnt lgkmcnt(5)
	v_mfma_f32_32x32x16_bf16 v[32:47], v[112:115], v[176:179], v[32:47]
	ds_read_b128 v[176:179], v244 offset:45056
	s_waitcnt lgkmcnt(5)
	v_mfma_f32_32x32x16_bf16 v[48:63], v[112:115], v[240:243], v[48:63]
	v_add_u32_e32 v244, v0, v201
	ds_read_b128 v[240:243], v244 offset:32768
	s_waitcnt lgkmcnt(5)
	v_mfma_f32_32x32x16_bf16 v[64:79], v[112:115], v[236:239], v[64:79]
	ds_read_b128 v[236:239], v244 offset:36864
	v_exp_f32_e32 v128, v120
	v_exp_f32_e32 v129, v121
	v_exp_f32_e32 v130, v122
	v_exp_f32_e32 v131, v123
	v_dot2c_f32_bf16 v192, s8, v112
	v_dot2c_f32_bf16 v193, s8, v113
	v_dot2c_f32_bf16 v192, s8, v114
	v_dot2c_f32_bf16 v193, s8, v115
	v_cvt_pk_bf16_f32 v112, v213, v214
	v_cvt_pk_bf16_f32 v113, v215, v216
	v_cvt_pk_bf16_f32 v114, v217, v218
	v_cvt_pk_bf16_f32 v115, v219, v220
	s_waitcnt lgkmcnt(5)
	s_nop 0
	v_mfma_f32_32x32x16_bf16 v[16:31], v[112:115], v[232:235], v[16:31]
	ds_read_b128 v[232:235], v244 offset:40960
	s_waitcnt lgkmcnt(5)
	v_mfma_f32_32x32x16_bf16 v[32:47], v[112:115], v[228:231], v[32:47]
	ds_read_b128 v[228:231], v244 offset:45056
	s_waitcnt lgkmcnt(5)
	v_mfma_f32_32x32x16_bf16 v[48:63], v[112:115], v[184:187], v[48:63]
	s_waitcnt lgkmcnt(4)
	v_mfma_f32_32x32x16_bf16 v[64:79], v[112:115], v[176:179], v[64:79]
	v_dot2c_f32_bf16 v192, s8, v112
	v_dot2c_f32_bf16 v193, s8, v113
	v_dot2c_f32_bf16 v192, s8, v114
	v_dot2c_f32_bf16 v193, s8, v115
	v_add_u32_e32 v0, v0, v201
	v_cvt_pk_bf16_f32 v112, v128, v129
	v_cvt_pk_bf16_f32 v113, v130, v131
	v_cvt_pk_bf16_f32 v114, v124, v125
	v_cvt_pk_bf16_f32 v115, v126, v127
	s_waitcnt lgkmcnt(3)
	s_nop 0
	v_mfma_f32_32x32x16_bf16 v[16:31], v[112:115], v[240:243], v[16:31]
	s_waitcnt lgkmcnt(2)
	v_mfma_f32_32x32x16_bf16 v[32:47], v[112:115], v[236:239], v[32:47]
	s_waitcnt lgkmcnt(1)
	v_mfma_f32_32x32x16_bf16 v[48:63], v[112:115], v[232:235], v[48:63]
	s_waitcnt lgkmcnt(0)
	v_mfma_f32_32x32x16_bf16 v[64:79], v[112:115], v[228:231], v[64:79]
	v_dot2c_f32_bf16 v192, s8, v112
	v_dot2c_f32_bf16 v193, s8, v113
	v_dot2c_f32_bf16 v192, s8, v114
	v_dot2c_f32_bf16 v193, s8, v115

; __device__ __forceinline__ float ex2(float v) { return __builtin_amdgcn_exp2f(v); }
; __device__ __forceinline__ int crow(int r, int h) { return (r & 3) + 8 * (r >> 2) + 4 * h; }
; #define MX3(a, b, c) __builtin_fmaxf(__builtin_fmaxf((a), (b)), (c))
; __device__ __forceinline__ void diff_unit(const Params& p, LAS unsigned char* lds, int b, int h, int qb, float lam) {
;     ...
;                 float mx;
;                 { float a0 = MX3(s0[0], s0[1], s1[0]), a1 = MX3(s0[2], s0[3], s1[1]); a0 = MX3(a0, s1[2], s1[3]);
; #pragma unroll
;                   for (int r = 4; r < 16; r += 4) { a0 = MX3(a0, s0[r], s0[r + 1]); a1 = MX3(a1, s0[r + 2], s0[r + 3]); a0 = MX3(a0, s1[r], s1[r + 1]); a1 = MX3(a1, s1[r + 2], s1[r + 3]); }
;                   mx = fmaxf(a0, a1); }
;                 { auto rr = __builtin_amdgcn_permlane32_swap(__float_as_uint(mx), __float_as_uint(mx), false, false); mx = fmaxf(__uint_as_float(rr[0]), __uint_as_float(rr[1])); }
;                 const bool first = (jt == 0);
;                 if (first || __any(mx > 8.0f)) {
;                     const float dl = first ? mx : fmaxf(mx, 0.f);
;                     m += dl;
; #pragma unroll
;                     for (int r = 0; r < 16; ++r) { s0[r] -= dl; s1[r] -= dl; }
; #pragma unroll
;                     for (int r = 0; r < 16; ++r) negm[r] = -m;
;                     if (!first) {
;                         const float alpha = ex2(-dl);
;                         int hl = hh; asm volatile("" : "+v"(hl));
; #pragma unroll
;                         for (int r = 0; r < 16; ++r) { const float a = __shfl(alpha, crow(r, hl)); L[r] *= a;
; #pragma unroll
;                             for (int db = 0; db < 4; ++db) O[db][r] *= a; }
;                     }
;                 }
.LBB0_308:
	s_nop 7
	v_max_f32_e32 v213, v129, v129
	v_max_f32_e32 v214, v128, v128
	v_max_f32_e32 v213, v214, v213
	v_max3_f32 v214, v130, v131, v113
	v_max3_f32 v213, v213, v112, v114
	v_max3_f32 v213, v213, v115, v132
	v_max3_f32 v214, v214, v134, v135
	v_max3_f32 v213, v213, v133, v116
	v_max3_f32 v214, v214, v118, v119
	v_max3_f32 v213, v213, v117, v136
	v_max3_f32 v214, v214, v138, v139
	v_max3_f32 v213, v213, v137, v120
	v_max3_f32 v214, v214, v122, v123
	v_max3_f32 v213, v213, v121, v140
	v_max3_f32 v214, v214, v142, v143
	v_max3_f32 v213, v213, v141, v124
	v_max3_f32 v214, v214, v126, v127
	v_max3_f32 v213, v213, v125, v214
	v_mov_b32_e32 v214, v213
	s_nop 1
	v_permlane32_swap_b32_e32 v213, v214
	v_max_f32_e32 v214, v214, v214
	v_max_f32_e32 v213, v213, v213
	v_max_f32_e32 v213, v213, v214
	v_cmp_lt_f32_e32 vcc, s70, v213
	s_cbranch_vccz .LBB0_303
	v_max_f32_e32 v96, v213, v213
	v_max_f32_e32 v214, 0, v96
	v_pk_add_f32 v[112:113], v[112:113], v[214:215] op_sel_hi:[1,0] neg_lo:[0,1] neg_hi:[0,1]
	v_pk_add_f32 v[114:115], v[114:115], v[214:215] op_sel_hi:[1,0] neg_lo:[0,1] neg_hi:[0,1]
	v_pk_add_f32 v[116:117], v[116:117], v[214:215] op_sel_hi:[1,0] neg_lo:[0,1] neg_hi:[0,1]
	v_pk_add_f32 v[118:119], v[118:119], v[214:215] op_sel_hi:[1,0] neg_lo:[0,1] neg_hi:[0,1]
	v_pk_add_f32 v[120:121], v[120:121], v[214:215] op_sel_hi:[1,0] neg_lo:[0,1] neg_hi:[0,1]
	v_pk_add_f32 v[122:123], v[122:123], v[214:215] op_sel_hi:[1,0] neg_lo:[0,1] neg_hi:[0,1]
	v_pk_add_f32 v[124:125], v[124:125], v[214:215] op_sel_hi:[1,0] neg_lo:[0,1] neg_hi:[0,1]
	v_pk_add_f32 v[126:127], v[126:127], v[214:215] op_sel_hi:[1,0] neg_lo:[0,1] neg_hi:[0,1]
	v_pk_add_f32 v[128:129], v[128:129], v[214:215] op_sel_hi:[1,0] neg_lo:[0,1] neg_hi:[0,1]
	v_pk_add_f32 v[130:131], v[130:131], v[214:215] op_sel_hi:[1,0] neg_lo:[0,1] neg_hi:[0,1]
	v_pk_add_f32 v[132:133], v[132:133], v[214:215] op_sel_hi:[1,0] neg_lo:[0,1] neg_hi:[0,1]
	v_pk_add_f32 v[134:135], v[134:135], v[214:215] op_sel_hi:[1,0] neg_lo:[0,1] neg_hi:[0,1]
	v_pk_add_f32 v[136:137], v[136:137], v[214:215] op_sel_hi:[1,0] neg_lo:[0,1] neg_hi:[0,1]
	v_pk_add_f32 v[138:139], v[138:139], v[214:215] op_sel_hi:[1,0] neg_lo:[0,1] neg_hi:[0,1]
	v_pk_add_f32 v[140:141], v[140:141], v[214:215] op_sel_hi:[1,0] neg_lo:[0,1] neg_hi:[0,1]
	v_pk_add_f32 v[142:143], v[142:143], v[214:215] op_sel_hi:[1,0] neg_lo:[0,1] neg_hi:[0,1]
	v_add_f32_e32 v212, v212, v214
	v_exp_f32_e64 v213, -v214
	v_mov_b32_e32 v214, v195
	v_xor_b32_e32 v96, 0x80000000, v212
	v_lshlrev_b32_e32 v221, 2, v214
	v_mul_f32_e32 v192, v192, v213
	v_mul_f32_e32 v193, v193, v213
	v_add_u32_e32 v222, 11, v221
	v_and_or_b32 v222, v222, 63, v194
	v_and_or_b32 v214, v221, 60, v194
	v_add_u32_e32 v218, 8, v221
	v_add_u32_e32 v219, 9, v221
	v_add_u32_e32 v220, 10, v221
	v_lshlrev_b32_e32 v230, 2, v222
	v_add_u32_e32 v222, 16, v221
	v_add_u32_e32 v223, 17, v221
	v_add_u32_e32 v224, 18, v221
	v_add_u32_e32 v225, 19, v221
	v_add_u32_e32 v226, 24, v221
	v_add_u32_e32 v227, 25, v221
	v_add_u32_e32 v228, 26, v221
	v_add_u32_e32 v221, 27, v221
	v_and_or_b32 v218, v218, 60, v194
	v_and_or_b32 v219, v219, 61, v194
	v_and_or_b32 v220, v220, 62, v194
	v_and_or_b32 v222, v222, 60, v194
	v_and_or_b32 v223, v223, 61, v194
	v_and_or_b32 v224, v224, 62, v194
	v_and_or_b32 v225, v225, 63, v194
	v_and_or_b32 v226, v226, 60, v194
	v_and_or_b32 v227, v227, 61, v194
	v_and_or_b32 v228, v228, 62, v194
	v_and_or_b32 v221, v221, 63, v194
	v_lshlrev_b32_e32 v217, 2, v214
	v_lshlrev_b32_e32 v218, 2, v218
	v_lshlrev_b32_e32 v219, 2, v219
	v_lshlrev_b32_e32 v220, 2, v220
	v_lshlrev_b32_e32 v222, 2, v222
	v_lshlrev_b32_e32 v223, 2, v223
	v_lshlrev_b32_e32 v224, 2, v224
	v_lshlrev_b32_e32 v225, 2, v225
	v_lshlrev_b32_e32 v226, 2, v226
	v_lshlrev_b32_e32 v227, 2, v227
	v_lshlrev_b32_e32 v228, 2, v228
	v_lshlrev_b32_e32 v221, 2, v221
	ds_bpermute_b32 v214, v217, v213
	ds_bpermute_b32 v215, v217, v213 offset:4
	ds_bpermute_b32 v216, v217, v213 offset:8
	ds_bpermute_b32 v217, v217, v213 offset:12
	ds_bpermute_b32 v218, v218, v213
	ds_bpermute_b32 v219, v219, v213
	ds_bpermute_b32 v220, v220, v213
	ds_bpermute_b32 v222, v222, v213
	ds_bpermute_b32 v224, v224, v213
	ds_bpermute_b32 v226, v226, v213
	ds_bpermute_b32 v228, v228, v213
	ds_bpermute_b32 v229, v221, v213
	ds_bpermute_b32 v227, v227, v213
	ds_bpermute_b32 v225, v225, v213
	ds_bpermute_b32 v223, v223, v213
	ds_bpermute_b32 v221, v230, v213
	v_mov_b32_e32 v97, v96
	v_mov_b32_e32 v98, v96
	v_mov_b32_e32 v99, v96
	v_mov_b32_e32 v100, v96
	v_mov_b32_e32 v101, v96
	v_mov_b32_e32 v102, v96
	v_mov_b32_e32 v103, v96
	v_mov_b32_e32 v104, v96
	v_mov_b32_e32 v105, v96
	v_mov_b32_e32 v106, v96
	v_mov_b32_e32 v107, v96
	v_mov_b32_e32 v108, v96
	v_mov_b32_e32 v109, v96
	v_mov_b32_e32 v110, v96
	v_mov_b32_e32 v111, v96
	s_waitcnt lgkmcnt(0)
	v_pk_mul_f32 v[30:31], v[30:31], v[228:229]
	v_pk_mul_f32 v[28:29], v[28:29], v[226:227]
	v_pk_mul_f32 v[26:27], v[26:27], v[224:225]
	v_pk_mul_f32 v[24:25], v[24:25], v[222:223]
	v_pk_mul_f32 v[22:23], v[22:23], v[220:221]
	v_pk_mul_f32 v[20:21], v[20:21], v[218:219]
	v_pk_mul_f32 v[18:19], v[18:19], v[216:217]
	v_pk_mul_f32 v[16:17], v[16:17], v[214:215]
	v_pk_mul_f32 v[46:47], v[46:47], v[228:229]
	v_pk_mul_f32 v[44:45], v[44:45], v[226:227]
	v_pk_mul_f32 v[42:43], v[42:43], v[224:225]
	v_pk_mul_f32 v[40:41], v[40:41], v[222:223]
	v_pk_mul_f32 v[38:39], v[38:39], v[220:221]
	v_pk_mul_f32 v[36:37], v[36:37], v[218:219]
	v_pk_mul_f32 v[34:35], v[34:35], v[216:217]
	v_pk_mul_f32 v[32:33], v[32:33], v[214:215]
	v_pk_mul_f32 v[62:63], v[62:63], v[228:229]
	v_pk_mul_f32 v[60:61], v[60:61], v[226:227]
	v_pk_mul_f32 v[58:59], v[58:59], v[224:225]
	v_pk_mul_f32 v[56:57], v[56:57], v[222:223]
	v_pk_mul_f32 v[54:55], v[54:55], v[220:221]
	v_pk_mul_f32 v[52:53], v[52:53], v[218:219]
	v_pk_mul_f32 v[50:51], v[50:51], v[216:217]
	v_pk_mul_f32 v[48:49], v[48:49], v[214:215]
	v_pk_mul_f32 v[78:79], v[78:79], v[228:229]
	v_pk_mul_f32 v[76:77], v[76:77], v[226:227]
	v_pk_mul_f32 v[74:75], v[74:75], v[224:225]
	v_pk_mul_f32 v[72:73], v[72:73], v[222:223]
	v_pk_mul_f32 v[70:71], v[70:71], v[220:221]
	v_pk_mul_f32 v[68:69], v[68:69], v[218:219]
	v_pk_mul_f32 v[66:67], v[66:67], v[216:217]
	v_pk_mul_f32 v[64:65], v[64:65], v[214:215]
	v_pk_mul_f32 v[94:95], v[94:95], v[228:229]
	v_pk_mul_f32 v[92:93], v[92:93], v[226:227]
	v_pk_mul_f32 v[90:91], v[90:91], v[224:225]
	v_pk_mul_f32 v[88:89], v[88:89], v[222:223]
	v_pk_mul_f32 v[86:87], v[86:87], v[220:221]
	v_pk_mul_f32 v[84:85], v[84:85], v[218:219]
	v_pk_mul_f32 v[82:83], v[82:83], v[216:217]
	v_pk_mul_f32 v[80:81], v[80:81], v[214:215]
	s_branch .LBB0_303
